# hand-written RWKV scan section (merged K=32 state MFMAs, 5 LDS-DMA loader waves) + second half of the operand prep moved into P3 on the non-scan workgroups, gated by per-tile release/acquire flags
# speedup vs baseline: 1.0341x; 1.0341x over previous
; #define LAS __attribute__((address_space(3)))
; __device__ __forceinline__ int lane_id() { int l__; asm volatile("v_mbcnt_lo_u32_b32 %0, -1, 0\n\tv_mbcnt_hi_u32_b32 %0, -1, %0" : "=v"(l__)); return l__; }
; __global__ void __launch_bounds__(NTHR, 2) hybrid_fwd(Args args) {
;     extern __shared__ __attribute__((aligned(16))) unsigned char lds[];
;     Frame F; F.lds = (LAS unsigned char*)lds; F.wave = __builtin_amdgcn_readfirstlane(threadIdx.x >> 6);
;     F.G = gridDim.x; F.gw = blockIdx.x * NWAVES + F.wave; F.NGW = F.G * NWAVES;
;     unsigned char* ws = args.ws;
;     volatile LAS unsigned* MISC = (volatile LAS unsigned*)(F.lds + MISC_OFF);
;     unsigned* ctl = (unsigned*)(ws + WS_CTL);
;     { int l_ = lane_id(); if (F.wave == 0 && l_ < 32) MISC[l_] = 0u; }
;     __syncthreads();
;     if (blockIdx.x == 0) { v4u* z = (v4u*)(ws + WS_CTL); const v4u zero = {0u, 0u, 0u, 0u}; const int t_ = F.wave * 64 + lane_id();
; #pragma unroll
;         for (int i = 0; i < 8; ++i) z[t_ + 512 * i] = zero; }
_Z10hybrid_fwd4Args:
	s_mov_b32 s94, s2
	s_mov_b32 s98, 0
	v_and_b32_e32 v1, 0x3ff, v0
	s_add_u32 s2, s0, 0xe0
	v_readfirstlane_b32 s93, v1
	s_addc_u32 s3, s1, 0
	s_cmp_lt_u32 s93, 64
	s_cselect_b64 s[4:5], -1, 0
	s_cmp_gt_u32 s93, 63
	s_load_dwordx8 s[84:91], s[0:1], 0xc0
	s_load_dword s97, s[0:1], 0xe0
	s_cselect_b64 s[6:7], -1, 0
	v_mbcnt_lo_u32_b32 v2, -1, 0
	v_mbcnt_hi_u32_b32 v2, -1, v2
	v_writelane_b32 v254, s6, 0
	v_cmp_gt_i32_e32 vcc, 32, v2
	s_nop 0
	v_writelane_b32 v254, s7, 1
	v_writelane_b32 v254, s4, 2
	s_and_b64 s[6:7], s[4:5], vcc
	s_nop 0
	v_writelane_b32 v254, s5, 3
	s_and_saveexec_b64 s[4:5], s[6:7]
	v_lshl_add_u32 v2, v2, 2, 0
	v_add_u32_e32 v2, 0x25800, v2
	v_mov_b32_e32 v3, 0
	ds_write_b32 v2, v3
	s_or_b64 exec, exec, s[4:5]
	s_cmp_lg_u32 s94, 0
	s_mov_b32 s4, 0
	s_waitcnt lgkmcnt(0)
	s_barrier
	s_cbranch_scc1 .LBB0_4
	s_and_b32 s5, s93, 0xffffffc0
	v_mbcnt_lo_u32_b32 v2, -1, 0
	v_mbcnt_hi_u32_b32 v2, -1, v2
	s_mov_b32 s6, s4
	v_add_u32_e32 v2, s5, v2
	v_ashrrev_i32_e32 v3, 31, v2
	v_lshl_add_u64 v[2:3], v[2:3], 4, s[90:91]
	s_mov_b32 s7, s4
	s_mov_b32 s5, s4
	v_mov_b64_e32 v[8:9], s[6:7]
	v_add_co_u32_e32 v4, vcc, 0x2000, v2
	v_mov_b64_e32 v[6:7], s[4:5]
	s_nop 0
	v_addc_co_u32_e32 v5, vcc, 0, v3, vcc
	global_store_dwordx4 v[4:5], v[6:9], off
	v_add_co_u32_e32 v4, vcc, 0x4000, v2
	global_store_dwordx4 v[2:3], v[6:9], off
	s_nop 0
	v_addc_co_u32_e32 v5, vcc, 0, v3, vcc
	global_store_dwordx4 v[4:5], v[6:9], off
	v_add_co_u32_e32 v4, vcc, 0x6000, v2
	s_nop 1
	v_addc_co_u32_e32 v5, vcc, 0, v3, vcc
	global_store_dwordx4 v[4:5], v[6:9], off
	v_add_co_u32_e32 v4, vcc, 0x8000, v2
	s_nop 1
	v_addc_co_u32_e32 v5, vcc, 0, v3, vcc
	global_store_dwordx4 v[4:5], v[6:9], off
	v_add_co_u32_e32 v4, vcc, 0xa000, v2
	s_nop 1
	v_addc_co_u32_e32 v5, vcc, 0, v3, vcc
	global_store_dwordx4 v[4:5], v[6:9], off
	v_add_co_u32_e32 v4, vcc, 0xc000, v2
	s_nop 1
	v_addc_co_u32_e32 v5, vcc, 0, v3, vcc
	v_add_co_u32_e32 v2, vcc, 0xe000, v2
	global_store_dwordx4 v[4:5], v[6:9], off
	s_nop 0
	v_addc_co_u32_e32 v3, vcc, 0, v3, vcc
	global_store_dwordx4 v[2:3], v[6:9], off

; #define LAS __attribute__((address_space(3)))
; #define LDS_WAIT() asm volatile("s_waitcnt lgkmcnt(0)" ::: "memory")
; #define LDS_WAIT() asm volatile("s_waitcnt lgkmcnt(0)" ::: "memory")
; __device__ __forceinline__ bf16x4s pk4s(f32x4 v) { return __builtin_bit_cast(bf16x4s, pk4(v)); }
; __device__ __forceinline__ void rw_chunk_prep(const Args& a, int head, int tc0, const LAS bf16* TDr, const LAS bf16* DAr, LAS unsigned char* lw_, int lane) {
;     ...
;     for (int e = 0; e < 4; ++e) { const int jp = 4 * rg + e; if (!(jp < j)) { AabT[e] = 0.f; AakT[e] = 0.f; } if (!(jp <= j)) { ArbT[e] = 0.f; ArkT[e] = 0.f; } }
;     *(LAS f32x4*)(MA + j * 16 + 4 * rg) = AabT;
;     LDS_WAIT(); asm volatile("" ::: "memory");
;     {   float x[16];
; #pragma unroll
;         for (int t = 0; t < 16; ++t) { float s = (t == j) ? 1.f : 0.f;
; #pragma unroll
;             for (int q = 0; q < 4; ++q) { if (4 * q < t) { const f32x4 row = *(const LAS f32x4*)(MA + t * 16 + 4 * q);
; #pragma unroll
;                 for (int e = 0; e < 4; ++e) if (4 * q + e < t) s += row[e] * x[4 * q + e]; } }
;             x[t] = s; }
;         if (rg == 0) {
; #pragma unroll
;             for (int t = 0; t < 16; ++t) MT[t * 16 + j] = x[t]; }
;     }
;     LDS_WAIT(); asm volatile("" ::: "memory");
;     const bf16x4s TmA = pk4s(*(const LAS f32x4*)(MT + j * 16 + 4 * kg));
;     const f32x4 z4 = {0.f, 0.f, 0.f, 0.f};
;     const bf16x4s aak = pk4s(AakT), arb = pk4s(ArbT), ark = pk4s(ArkT);
;     bf16x4s idb; { v2u u; u.x = ((4 * kg + 0 == j) ? 0x3F80u : 0u) | ((4 * kg + 1 == j) ? 0x3F800000u : 0u); u.y = ((4 * kg + 2 == j) ? 0x3F80u : 0u) | ((4 * kg + 3 == j) ? 0x3F800000u : 0u); idb = __builtin_bit_cast(bf16x4s, u); }
; __global__ void __launch_bounds__(NTHR, 2) hybrid_fwd(Args args) {
;     ...
;         for (int tile = blockIdx.x; tile < T / 32; tile += F.G) p2_rwprep_tile(F, args, tile * 32); }
.LBB0_320:
	s_cmpk_lt_i32 s94, 0x200
	s_cselect_b64 s[0:1], -1, 0
	v_writelane_b32 v254, s0, 41
	s_cmpk_gt_i32 s94, 0x1ff
	s_nop 0
	v_writelane_b32 v254, s1, 42
	s_cbranch_scc1 .LBB0_347
	v_writelane_b32 v255, s36, 8
	v_writelane_b32 v255, s37, 9
	v_writelane_b32 v255, s38, 10
	v_writelane_b32 v255, s39, 11
	v_writelane_b32 v255, s40, 12
	v_writelane_b32 v255, s41, 13
	v_writelane_b32 v255, s42, 14
	v_writelane_b32 v255, s43, 15
	v_writelane_b32 v255, s44, 16
	v_writelane_b32 v255, s45, 17
	v_writelane_b32 v255, s46, 18
	v_writelane_b32 v255, s47, 19
	v_writelane_b32 v255, s48, 20
	v_writelane_b32 v255, s49, 21
	v_writelane_b32 v255, s50, 22
	v_writelane_b32 v255, s51, 23
.Lrw_again:
	v_cmp_eq_u32_e64 s[22:23], 15, v11
	v_lshlrev_b32_e32 v6, 2, v10
	v_and_b32_e32 v1, 60, v6
	v_cndmask_b32_e64 v167, 0, 1.0, s[22:23]
	v_cmp_eq_u32_e64 s[22:23], 1, v11
	v_lshlrev_b32_e32 v66, 2, v1
	v_lshlrev_b32_e32 v2, 7, v64
	v_cndmask_b32_e64 v168, 0, 1.0, s[22:23]
	v_cmp_eq_u32_e64 s[22:23], 2, v11
	v_lshlrev_b32_e32 v1, 1, v1
	v_ashrrev_i32_e32 v4, 4, v10
	v_cndmask_b32_e64 v169, 0, 1.0, s[22:23]
	v_cmp_eq_u32_e64 s[22:23], 3, v11
	v_add3_u32 v65, 0, v2, v1
	v_lshlrev_b32_e32 v2, 3, v4
	v_cndmask_b32_e64 v170, 0, 1.0, s[22:23]
	v_cmp_eq_u32_e64 s[22:23], 4, v11
	v_ashrrev_i32_e32 v3, 31, v2
	v_mbcnt_hi_u32_b32 v1, -1, v156
	v_cndmask_b32_e64 v171, 0, 1.0, s[22:23]
	v_cmp_eq_u32_e64 s[22:23], 5, v11
	v_lshlrev_b64 v[2:3], 1, v[2:3]
	v_and_b32_e32 v1, 64, v1
	v_cndmask_b32_e64 v172, 0, 1.0, s[22:23]
	v_cmp_eq_u32_e64 s[22:23], 6, v11
	v_lshl_add_u64 v[74:75], s[6:7], 0, v[2:3]
	v_lshl_add_u64 v[76:77], s[8:9], 0, v[2:3]
	v_add_u32_e32 v2, 48, v10
	v_cndmask_b32_e64 v173, 0, 1.0, s[22:23]
	v_cmp_eq_u32_e64 s[22:23], 7, v11
	v_and_or_b32 v2, v2, 63, v1
	v_lshlrev_b32_e32 v158, 2, v2
	v_cndmask_b32_e64 v174, 0, 1.0, s[22:23]
	v_cmp_eq_u32_e64 s[22:23], 8, v11
	v_and_or_b32 v2, v10, 63, v1
	s_mul_i32 s0, s92, 0x2800
	v_cndmask_b32_e64 v175, 0, 1.0, s[22:23]
	v_cmp_eq_u32_e64 s[22:23], 9, v11
	v_lshlrev_b32_e32 v2, 2, v2
	s_add_i32 s33, s0, 0
	v_cndmask_b32_e64 v176, 0, 1.0, s[22:23]
	v_cmp_eq_u32_e64 s[22:23], 10, v11
	v_xor_b32_e32 v159, 0x80, v2
	v_or_b32_e32 v1, v1, v11
	v_mov_b32_e32 v2, 0xc0
	v_cndmask_b32_e64 v177, 0, 1.0, s[22:23]
	v_cmp_eq_u32_e64 s[22:23], 11, v11
	v_lshlrev_b32_e32 v157, 2, v4
	v_lshl_or_b32 v160, v1, 2, v2
	v_lshl_add_u32 v1, v11, 3, s33
	v_cndmask_b32_e64 v178, 0, 1.0, s[22:23]
	v_cmp_eq_u32_e64 s[22:23], 12, v11
	v_and_b32_e32 v7, -16, v10
	v_cmp_lt_i32_e64 s[4:5], 0, v4
	v_cmp_lt_i32_e64 s[6:7], 1, v4
	v_lshl_add_u32 v161, v4, 9, v1
	v_or_b32_e32 v2, 1, v157
	v_or_b32_e32 v3, 2, v157
	v_or_b32_e32 v4, 3, v157
	v_cndmask_b32_e64 v179, 0, 1.0, s[22:23]
	v_cmp_eq_u32_e64 s[22:23], 13, v11
	v_lshlrev_b32_e32 v5, 7, v11
	v_lshl_add_u32 v162, v2, 7, v1
	v_lshl_add_u32 v163, v3, 7, v1
	v_lshl_add_u32 v164, v4, 7, v1
	v_add_u32_e32 v1, s33, v7
	v_cndmask_b32_e64 v180, 0, 1.0, s[22:23]
	v_cmp_eq_u32_e64 s[22:23], 14, v11
	v_add_u32_e32 v165, v1, v5
	v_lshl_add_u32 v166, v11, 6, v1
	v_cndmask_b32_e64 v181, 0, 1.0, s[22:23]
	v_mov_b32_e32 v1, 0x3f80
	v_cmp_eq_u32_e64 s[22:23], v157, v11
	v_add3_u32 v155, 0, v5, v7
	v_cmp_lt_i32_e32 vcc, v2, v11
	v_cndmask_b32_e64 v5, 0, v1, s[22:23]
	v_cmp_eq_u32_e64 s[22:23], v2, v11
	v_mov_b32_e32 v67, 0
	v_cmp_lt_i32_e64 s[20:21], v3, v11
	v_cndmask_b32_e64 v2, 0, 1.0, s[22:23]
	v_cmp_eq_u32_e64 s[22:23], v3, v11
	v_or_b32_e32 v78, v2, v5
	v_cmp_gt_i32_e64 s[12:13], v3, v11
	v_cndmask_b32_e64 v1, 0, v1, s[22:23]
	v_cmp_eq_u32_e64 s[22:23], v4, v11
	v_lshl_add_u64 v[68:69], s[14:15], 0, v[66:67]
	v_cmp_lt_i32_e64 s[14:15], v4, v11
	v_cndmask_b32_e64 v2, 0, 1.0, s[22:23]
	v_or_b32_e32 v79, v1, v2
	v_lshlrev_b32_e32 v2, 3, v10
	v_ashrrev_i32_e32 v3, 31, v2
	v_cmp_gt_i32_e64 s[16:17], v4, v11
	v_lshl_add_u64 v[4:5], s[90:91], 0, v[2:3]
	s_mov_b64 s[2:3], 0x19000000
	s_lshl_b32 s34, s92, 1
	v_lshl_add_u64 v[80:81], v[4:5], 0, s[2:3]
	s_mov_b64 s[2:3], 0x1b000000
	s_add_u32 s35, s90, 0x3d00000
	v_lshl_add_u64 v[82:83], v[4:5], 0, s[2:3]
	v_lshl_add_u64 v[2:3], s[88:89], 0, v[2:3]
	s_mov_b64 s[2:3], 0x4000000
	v_lshl_add_u64 v[72:73], s[36:37], 0, v[66:67]
	s_addc_u32 s36, s91, 0
	v_lshl_add_u64 v[84:85], v[2:3], 0, s[2:3]
	s_mov_b64 s[2:3], 0x6000000
	v_ashrrev_i32_e32 v1, 31, v0
	v_lshl_add_u64 v[86:87], v[2:3], 0, s[2:3]
	s_mov_b64 s[2:3], 0x1d000000
	v_lshl_add_u64 v[90:91], s[88:89], 0, v[0:1]
	s_add_u32 s37, s90, 0x1f000000
	v_and_b32_e32 v0, 3, v10
	v_lshl_add_u64 v[88:89], v[4:5], 0, s[2:3]
	s_mov_b64 s[2:3], 0x2000000
	s_addc_u32 s40, s91, 0
	v_and_or_b32 v0, v6, 48, v0
	s_or_b64 s[20:21], s[14:15], s[20:21]
	v_lshl_add_u64 v[70:71], s[82:83], 0, v[66:67]
	s_mov_b32 s1, 0
	v_lshlrev_b32_e32 v154, 2, v11
	v_cmp_eq_u32_e64 s[24:25], 0, v11
	v_cmp_lt_i32_e64 s[8:9], v157, v11
	v_cmp_gt_i32_e64 s[10:11], v157, v11
	v_cmp_gt_u32_e64 s[18:19], 16, v10
	v_add_u32_e32 v182, s33, v6
	v_lshl_add_u64 v[92:93], v[90:91], 0, s[2:3]
	v_or3_b32 v94, v10, v6, 12
	v_mov_b32_e32 v95, v67
	s_mov_b32 s41, 0xc1700000
	s_movk_i32 s44, 0x1800
	s_movk_i32 s45, 0x1000
	s_mov_b32 s52, 0xbfb8aa3b
	s_mov_b32 s53, 0x800000
	s_mov_b32 s54, 0x3f317217
	s_mov_b32 s55, 0x7f800000
	v_lshlrev_b32_e32 v183, 2, v0
	v_mov_b32_e32 v184, 0x41700000
	v_mov_b32_e32 v185, 0x41b17218
	s_or_b64 s[22:23], s[20:21], vcc
	s_add_i32 s101, s94, 0xc0
	s_cmp_eq_u32 s98, 1
	s_cselect_b32 s56, s101, s94
	s_branch .LBB0_323
.LBB0_322:
	s_waitcnt vmcnt(0)
	s_barrier
	s_cmp_lg_u32 s98, 1
	s_cbranch_scc1 .Lrw_step
	s_cmp_lg_u32 s92, 0
	s_cbranch_scc1 .Lrw_step
	buffer_wbl2 sc1
	s_waitcnt vmcnt(0)
	s_lshl_b32 s101, s56, 2
	s_add_i32 s101, s101, 0x8000
	v_mov_b32_e32 v204, s101
	v_mov_b32_e32 v205, 1
	s_mov_b64 exec, 1
	global_atomic_add v204, v205, s[90:91]
	s_mov_b64 exec, -1
.Lrw_step:
	s_movk_i32 s100, 0xff
	s_cmp_eq_u32 s98, 1
	s_cselect_b32 s101, 0xc0, s97
	s_cselect_b32 s100, 0x1ff, s100
	s_add_i32 s56, s56, s101
	s_cmp_gt_i32 s56, s100
	s_cbranch_scc1 .LBB0_347

; __device__ __forceinline__ unsigned xb_add(unsigned* p, unsigned v) { return __hip_atomic_fetch_add(p, v, __ATOMIC_RELAXED, __HIP_MEMORY_SCOPE_AGENT); }
; __device__ __forceinline__ void xcd_barrier(const XcdBarrier& b, int tid) {
;     asm volatile("s_waitcnt vmcnt(0)" ::: "memory");
;     __syncthreads();
;     if (tid == 0) {
;         unsigned* bar = b.bar;
;         __builtin_amdgcn_s_waitcnt(0);
;         unsigned nloc = b.st[0], nx = b.st[1];
;         if (nloc == 0u) { xcd_barrier_complete(bar, b.x, nloc, nx); b.st[0] = nloc; b.st[1] = nx; }
;         const unsigned old = xb_add(&bar[XB_XSUB(b.x)], 1u);
.LBB0_347:
	s_cmp_eq_u32 s98, 1
	s_cbranch_scc1 .Lrw_late_done
	v_mbcnt_lo_u32_b32 v0, -1, 0
	v_mbcnt_hi_u32_b32 v0, -1, v0
	v_readlane_b32 s0, v254, 25
	s_waitcnt vmcnt(0)
	s_nop 0
	v_sub_u32_e32 v0, 0, v0
	v_cmp_eq_u32_e32 vcc, s0, v0
	s_barrier
	s_and_saveexec_b64 s[0:1], vcc
	v_readlane_b32 s42, v254, 26
	v_readlane_b32 s43, v254, 27
	s_cbranch_execz .LBB0_399
	s_add_i32 s2, 0, 0x25820
	v_mov_b32_e32 v0, s2
	s_waitcnt vmcnt(0) expcnt(0) lgkmcnt(0)
	ds_read_b32 v2, v0
	s_add_i32 s2, 0, 0x25824
	v_mov_b32_e32 v0, s2
	ds_read_b32 v0, v0
	s_waitcnt lgkmcnt(1)
	v_cmp_ne_u32_e32 vcc, 0, v2
	s_cbranch_vccnz .LBB0_363
	v_readlane_b32 s2, v254, 4
	v_readlane_b32 s3, v254, 5
	s_mul_i32 s33, s3, s97
	s_mul_i32 s33, s33, s2
	s_add_u32 s2, s90, 0x4200
	s_addc_u32 s3, s91, 0
	s_add_u32 s4, s90, 0x4400
	s_addc_u32 s5, s91, 0
	s_add_u32 s6, s90, 0x4500
	s_addc_u32 s7, s91, 0
	s_add_u32 s8, s90, 0x4600
	s_addc_u32 s9, s91, 0
	s_add_u32 s10, s90, 0x4700
	s_addc_u32 s11, s91, 0
	s_add_u32 s12, s90, 0x4800
	s_addc_u32 s13, s91, 0
	s_add_u32 s14, s90, 0x4900
	s_addc_u32 s15, s91, 0
	s_add_u32 s16, s90, 0x4a00
	s_addc_u32 s17, s91, 0
	s_add_u32 s18, s90, 0x4b00
	s_addc_u32 s19, s91, 0
	s_add_u32 s20, s90, 0x4c00
	s_addc_u32 s21, s91, 0
	s_add_u32 s22, s90, 0x4d00
	s_addc_u32 s23, s91, 0
	s_add_u32 s24, s90, 0x4e00
	s_addc_u32 s25, s91, 0
	s_add_u32 s26, s90, 0x4f00
	s_addc_u32 s27, s91, 0
	s_add_u32 s34, s90, 0x5000
	s_addc_u32 s35, s91, 0
	s_add_u32 s36, s90, 0x5100
	s_addc_u32 s37, s91, 0
	s_add_u32 s38, s90, 0x5200
	s_addc_u32 s39, s91, 0
	s_add_u32 s40, s90, 0x5300
	s_addc_u32 s41, s91, 0
	s_mov_b32 s48, 1
	v_mov_b32_e32 v16, 0
	s_branch .LBB0_351

; #define SP_BAR() asm volatile("s_waitcnt lgkmcnt(0)\n\ts_barrier" ::: "memory")
; #define SP_WAIT() asm volatile("s_waitcnt vmcnt(36)" ::: "memory")
; __device__ __forceinline__ void p3_rwkv_state(Frame& F, const Args& a) {
;     constexpr int NC = T / 16;
;     const int xcd_ = blockIdx.x & 7, sl_ = blockIdx.x >> 3, head = 2 * xcd_ + (sl_ >> 2), ib = sl_ & 3, lane = F.lane, rg = lane >> 4;
;     const unsigned lds0 = (unsigned)(uintptr_t)F.lds;
;     const bool loader = F.wave >= 1 && F.wave <= 3; const int lw = F.wave - 1;
;     ...
;     if (loader) {
;         DmaPtrs P; rw_dma_init(a, P, head, ib, lw, lane);
;         for (int n = 0; n < SP_D; ++n) rw_dma_issue(P, lw, lane, lds0 + (unsigned)(n % SP_R) * SP_SLOT);
;         SP_WAIT();
;         SP_BAR();
;         for (int n = 0; n < NC; n += 2) {
;             if (n + SP_D + 1 < NC) { rw_dma_issue(P, lw, lane, lds0 + (unsigned)((n + SP_D) % SP_R) * SP_SLOT); rw_dma_issue(P, lw, lane, lds0 + (unsigned)((n + SP_D + 1) % SP_R) * SP_SLOT); SP_WAIT(); }
;             else asm volatile("s_waitcnt vmcnt(0)" ::: "memory");
;             SP_BAR();
;         }
; __global__ void __launch_bounds__(NTHR, 2) hybrid_fwd(Args args) {
;     ...
;     {   if ((int)blockIdx.x < NRWB) p3_rwkv_state(F, args);
.LBB0_399:
	s_or_b64 exec, exec, s[0:1]
	s_waitcnt lgkmcnt(0)
	s_barrier
	v_mbcnt_lo_u32_b32 v76, -1, 0
	v_mbcnt_hi_u32_b32 v76, -1, v76
	s_cmp_lt_i32 s94, 64
	s_cbranch_scc0 .Lrw_late_entry
	s_lshl_b32 s0, s94, 1
	s_and_b32 s0, s0, 14
	s_lshr_b32 s1, s94, 5
	s_add_i32 s0, s0, s1
	s_bfe_u32 s4, s94, 0x20003
	s_mov_b32 s19, m0
	s_cmp_eq_u32 s92, 0
	s_cbranch_scc1 .Lscan_consumer
	s_cmp_eq_u32 s92, 6
	s_cbranch_scc1 .Lscan_ldsmall
	s_cmp_eq_u32 s92, 4
	s_cbranch_scc1 .Lscan_idle
	s_cmp_eq_u32 s92, 7
	s_cbranch_scc1 .Lscan_idle
	s_add_i32 s3, s92, -1
	s_min_u32 s3, s3, 3
	s_lshl_b32 s2, s0, 11
	s_lshl_b32 s5, s3, 25
	s_add_u32 s2, s2, s5
	s_add_u32 s12, s88, s2
	s_addc_u32 s13, s89, 0
	v_lshlrev_b32_e32 v0, 4, v76
	v_mov_b32_e32 v1, 0
	v_lshl_add_u64 v[2:3], s[12:13], 0, v[0:1]
	s_lshl_b32 s14, s3, 11
	s_mov_b64 s[6:7], 0x8000
	s_mov_b32 s15, 0
	s_mov_b32 s18, 0
.Lscan_ldbig_pro:
	s_add_i32 s16, s15, s14
	s_mov_b32 m0, s16
	s_add_i32 s15, s15, 0x2800
	global_load_lds_dwordx4 v[2:3], off
	global_load_lds_dwordx4 v[2:3], off offset:1024
	s_cmp_eq_u32 s15, 0x25800
	s_cselect_b32 s15, 0, s15
	v_lshl_add_u64 v[2:3], v[2:3], 0, s[6:7]
	s_add_i32 s18, s18, 1
	s_cmp_lt_u32 s18, 12
	s_cbranch_scc1 .Lscan_ldbig_pro
	s_waitcnt vmcnt(18)
	s_barrier
	s_mov_b32 s18, 0
	s_movk_i32 s17, 0x100
.Lscan_ldbig_loop:
	s_cmpk_gt_u32 s18, 0x3f2
	s_cbranch_scc1 .Lscan_ldbig_tail
.Lscan_ldbig_chk:
	s_lshr_b32 s24, s18, 1
	s_add_i32 s24, s24, 6
	s_cmp_lt_u32 s24, s17
	s_cbranch_scc1 .Lscan_ldbig_go
	v_add_u32_e32 v12, s17, v76
	v_lshlrev_b32_e32 v13, 2, v12
	v_add_u32_e32 v13, 0x8000, v13
	global_load_dword v13, v13, s[90:91] sc1
	s_movk_i32 s24, 0x1ff
	s_waitcnt vmcnt(0)
	v_cmp_ne_u32_e64 s[20:21], 0, v13
	v_cmp_lt_u32_e64 s[22:23], s24, v12
	s_nop 1
	s_or_b64 s[20:21], s[20:21], s[22:23]
	s_not_b64 s[20:21], s[20:21]
	s_ff1_i32_b64 s24, s[20:21]
	s_cmp_eq_u32 s24, -1
	s_cselect_b32 s24, 64, s24
	s_add_i32 s17, s17, s24
	buffer_inv sc1
	s_waitcnt vmcnt(0)
	s_cmp_lg_u32 s24, 0
	s_cbranch_scc1 .Lscan_ldbig_chk
	s_sleep 8
	s_branch .Lscan_ldbig_chk
.Lscan_ldbig_go:
	s_add_i32 s16, s15, s14
	s_mov_b32 m0, s16
	s_add_i32 s15, s15, 0x2800
	global_load_lds_dwordx4 v[2:3], off
	global_load_lds_dwordx4 v[2:3], off offset:1024
	s_cmp_eq_u32 s15, 0x25800
	s_cselect_b32 s15, 0, s15
	v_lshl_add_u64 v[2:3], v[2:3], 0, s[6:7]
	s_add_i32 s16, s15, s14
	s_mov_b32 m0, s16
	s_add_i32 s15, s15, 0x2800
	global_load_lds_dwordx4 v[2:3], off
	global_load_lds_dwordx4 v[2:3], off offset:1024
	s_cmp_eq_u32 s15, 0x25800
	s_cselect_b32 s15, 0, s15
	v_lshl_add_u64 v[2:3], v[2:3], 0, s[6:7]
	s_waitcnt vmcnt(18)
	s_branch .Lscan_ldbig_bar

; #define SP_BAR() asm volatile("s_waitcnt lgkmcnt(0)\n\ts_barrier" ::: "memory")
; #define SP_WAIT() asm volatile("s_waitcnt vmcnt(36)" ::: "memory")
; __device__ __forceinline__ void rw_dma_init(const Args& a, DmaPtrs& P, int head, int ib, int lw, int lane) {
;     const unsigned char* outb = (const unsigned char*)a.out; const unsigned char* ws = a.ws; const size_t c0 = (size_t)head * 2048;
;     if (lw == 0) { P.p[0] = outb + OUT_W1A + c0 + lane * 16; P.p[1] = P.p[0] + 1024; P.p[2] = outb + OUT_QA + c0 + lane * 16; P.p[3] = P.p[2] + 1024; P.off[0] = 0u; P.off[1] = 1024u; P.off[2] = 2048u; P.off[3] = 3072u; }
;     else if (lw == 1) { P.p[0] = outb + OUT_BT + c0 + lane * 16; P.p[1] = P.p[0] + 1024; P.p[2] = outb + OUT_KT + c0 + lane * 16; P.p[3] = P.p[2] + 1024; P.off[0] = 4096u; P.off[1] = 5120u; P.off[2] = 6144u; P.off[3] = 7168u; }
;     else { const int l32 = lane & 31; P.p[0] = ws + WS_U0 + c0 + ib * 512 + l32 * 16; P.p[1] = ws + WS_Y0 + c0 + ib * 512 + l32 * 16; P.p[2] = ws + WS_VS + c0 + ib * 512 + l32 * 16; P.p[3] = ws + WS_DD + (size_t)head * 256 + (lane & 15) * 16;
;            P.off[0] = 8192u; P.off[1] = 8704u; P.off[2] = 9216u; P.off[3] = 9728u; }
; }
; __device__ __forceinline__ void rw_dma_issue(DmaPtrs& P, int lw, int lane, unsigned slot_lds) {
;     if (lw < 2) {
; #pragma unroll
;         for (int q = 0; q < 4; ++q) attn_body::glds16(P.p[q], (unsigned)__builtin_amdgcn_readfirstlane(slot_lds + P.off[q]));
;     } else {
;         if (lane < 32) {
; #pragma unroll
;             for (int q = 0; q < 3; ++q) attn_body::glds16(P.p[q], (unsigned)__builtin_amdgcn_readfirstlane(slot_lds + P.off[q])); }
;         if (lane < 16) attn_body::glds16(P.p[3], (unsigned)__builtin_amdgcn_readfirstlane(slot_lds + P.off[3]));
;     }
; #pragma unroll
;     for (int q = 0; q < 4; ++q) P.p[q] += (lw == 2 && q == 3) ? 16 * 256 : 16 * 2048;
; }
; __device__ __forceinline__ void p3_rwkv_state(Frame& F, const Args& a) {
;     ...
;         for (int n = 0; n < NC; n += 2) {
;             if (n + SP_D + 1 < NC) { rw_dma_issue(P, lw, lane, lds0 + (unsigned)((n + SP_D) % SP_R) * SP_SLOT); rw_dma_issue(P, lw, lane, lds0 + (unsigned)((n + SP_D + 1) % SP_R) * SP_SLOT); SP_WAIT(); }
;             else asm volatile("s_waitcnt vmcnt(0)" ::: "memory");
;             SP_BAR();
;         }
.Lscan_ldbig_bar:
	s_barrier
	s_add_i32 s18, s18, 2
	s_cmpk_lt_u32 s18, 0x400
	s_cbranch_scc1 .Lscan_ldbig_loop
	s_mov_b32 m0, s19
	s_branch .LBB0_456
.Lscan_ldsmall:
	s_lshl_b32 s2, s0, 11
	s_lshl_b32 s5, s4, 9
	s_add_u32 s2, s2, s5
	s_add_u32 s12, s90, s2
	s_addc_u32 s13, s91, 0
	v_and_b32_e32 v0, 31, v76
	v_lshlrev_b32_e32 v0, 4, v0
	v_mov_b32_e32 v1, 0
	v_lshl_add_u64 v[0:1], s[12:13], 0, v[0:1]
	s_mov_b64 s[2:3], 0x19000000
	v_lshl_add_u64 v[2:3], v[0:1], 0, s[2:3]
	s_mov_b64 s[2:3], 0x1afffe00
	v_lshl_add_u64 v[4:5], v[0:1], 0, s[2:3]
	s_mov_b64 s[2:3], 0x1cfffc00
	v_lshl_add_u64 v[6:7], v[0:1], 0, s[2:3]
	s_lshl_b32 s2, s0, 8
	s_add_u32 s12, s90, s2
	s_addc_u32 s13, s91, 0
	v_and_b32_e32 v8, 15, v76
	v_lshlrev_b32_e32 v8, 4, v8
	v_mov_b32_e32 v9, 0
	v_lshl_add_u64 v[8:9], s[12:13], 0, v[8:9]
	s_mov_b64 s[2:3], 0x1efffa00
	v_lshl_add_u64 v[8:9], v[8:9], 0, s[2:3]
	s_mov_b64 s[6:7], 0x8000
	s_mov_b64 s[10:11], 0x1000
	s_mov_b32 s15, 0
	s_mov_b32 s18, 0
.Lscan_ldsmall_pro:
	s_add_i32 s16, s15, 0x2000
	s_mov_b32 m0, s16
	s_mov_b32 exec_hi, 0
	s_add_i32 s15, s15, 0x2800
	global_load_lds_dwordx4 v[2:3], off
	global_load_lds_dwordx4 v[4:5], off offset:512
	global_load_lds_dwordx4 v[6:7], off offset:1024
	s_mov_b32 exec_lo, 0xffff
	s_cmp_eq_u32 s15, 0x25800
	global_load_lds_dwordx4 v[8:9], off offset:1536
	s_mov_b64 exec, -1
	s_cselect_b32 s15, 0, s15
	v_lshl_add_u64 v[2:3], v[2:3], 0, s[6:7]
	v_lshl_add_u64 v[4:5], v[4:5], 0, s[6:7]
	v_lshl_add_u64 v[6:7], v[6:7], 0, s[6:7]
	v_lshl_add_u64 v[8:9], v[8:9], 0, s[10:11]
	s_add_i32 s18, s18, 1
	s_cmp_lt_u32 s18, 12
	s_cbranch_scc1 .Lscan_ldsmall_pro
	s_waitcnt vmcnt(36)
	s_barrier
	s_mov_b32 s18, 0
	s_movk_i32 s17, 0x100

; #define SP_BAR() asm volatile("s_waitcnt lgkmcnt(0)\n\ts_barrier" ::: "memory")
; #define SP_WAIT() asm volatile("s_waitcnt vmcnt(36)" ::: "memory")
; __device__ __forceinline__ void rw_dma_issue(DmaPtrs& P, int lw, int lane, unsigned slot_lds) {
;     if (lw < 2) {
; #pragma unroll
;         for (int q = 0; q < 4; ++q) attn_body::glds16(P.p[q], (unsigned)__builtin_amdgcn_readfirstlane(slot_lds + P.off[q]));
;     } else {
;         if (lane < 32) {
; #pragma unroll
;             for (int q = 0; q < 3; ++q) attn_body::glds16(P.p[q], (unsigned)__builtin_amdgcn_readfirstlane(slot_lds + P.off[q])); }
;         if (lane < 16) attn_body::glds16(P.p[3], (unsigned)__builtin_amdgcn_readfirstlane(slot_lds + P.off[3]));
; __device__ __forceinline__ void p3_rwkv_state(Frame& F, const Args& a) {
;     ...
;         for (int n = 0; n < NC; n += 2) {
;             if (n + SP_D + 1 < NC) { rw_dma_issue(P, lw, lane, lds0 + (unsigned)((n + SP_D) % SP_R) * SP_SLOT); rw_dma_issue(P, lw, lane, lds0 + (unsigned)((n + SP_D + 1) % SP_R) * SP_SLOT); SP_WAIT(); }
;             else asm volatile("s_waitcnt vmcnt(0)" ::: "memory");
;             SP_BAR();
;         }
.Lscan_ldsmall_go:
	s_add_i32 s16, s15, 0x2000
	s_mov_b32 m0, s16
	s_mov_b32 exec_hi, 0
	s_add_i32 s15, s15, 0x2800
	global_load_lds_dwordx4 v[2:3], off
	global_load_lds_dwordx4 v[4:5], off offset:512
	global_load_lds_dwordx4 v[6:7], off offset:1024
	s_mov_b32 exec_lo, 0xffff
	s_cmp_eq_u32 s15, 0x25800
	global_load_lds_dwordx4 v[8:9], off offset:1536
	s_mov_b64 exec, -1
	s_cselect_b32 s15, 0, s15
	v_lshl_add_u64 v[2:3], v[2:3], 0, s[6:7]
	v_lshl_add_u64 v[4:5], v[4:5], 0, s[6:7]
	v_lshl_add_u64 v[6:7], v[6:7], 0, s[6:7]
	v_lshl_add_u64 v[8:9], v[8:9], 0, s[10:11]
	s_add_i32 s16, s15, 0x2000
	s_mov_b32 m0, s16
	s_mov_b32 exec_hi, 0
	s_add_i32 s15, s15, 0x2800
	global_load_lds_dwordx4 v[2:3], off
	global_load_lds_dwordx4 v[4:5], off offset:512
	global_load_lds_dwordx4 v[6:7], off offset:1024
	s_mov_b32 exec_lo, 0xffff
	s_cmp_eq_u32 s15, 0x25800
	global_load_lds_dwordx4 v[8:9], off offset:1536
	s_mov_b64 exec, -1
	s_cselect_b32 s15, 0, s15
	v_lshl_add_u64 v[2:3], v[2:3], 0, s[6:7]
	v_lshl_add_u64 v[4:5], v[4:5], 0, s[6:7]
	v_lshl_add_u64 v[6:7], v[6:7], 0, s[6:7]
	v_lshl_add_u64 v[8:9], v[8:9], 0, s[10:11]
	s_waitcnt vmcnt(36)
	s_branch .Lscan_ldsmall_bar

; __device__ __forceinline__ bf16x8 pk8s(f32x4 a, f32x4 b) { v4u u; u.x = pk2(a.x, a.y); u.y = pk2(a.z, a.w); u.z = pk2(b.x, b.y); u.w = pk2(b.z, b.w); return __builtin_bit_cast(bf16x8, u); }
; #define SP_BAR() asm volatile("s_waitcnt lgkmcnt(0)\n\ts_barrier" ::: "memory")
; __device__ __forceinline__ void p3_rwkv_state(Frame& F, const Args& a) {
;     ...
;     } else if (F.wave == 0) {
;         bf16* YR = (bf16*)(a.ws + WS_YR) + head * 64 + 4 * (lane & 15) + ib;
;         f32x4 H[4]; bf16x8 Hb[2];
; #pragma unroll
;         for (int t = 0; t < 4; ++t) H[t] = (f32x4){0.f, 0.f, 0.f, 0.f};
;         Hb[0] = pk8s(H[0], H[1]); Hb[1] = pk8s(H[2], H[3]);
;         ChunkOps C, N;
;         SP_BAR();
;         rw_slot_read(C, F.lds, ib, lane);
;     ...
;     } else {
;         for (int n = 0; n < NC / 2 + 1; ++n) SP_BAR();
;     }
.Lscan_idle:
	s_movk_i32 s1, 0x201
.Lscan_idle_loop:
	s_barrier
	s_add_i32 s1, s1, -1
	s_cmp_lg_u32 s1, 0
	s_cbranch_scc1 .Lscan_idle_loop
	s_branch .LBB0_456
.Lscan_consumer:
	s_lshl_b32 s1, s0, 7
	s_add_u32 s8, s72, s1
	s_addc_u32 s9, s73, 0
	s_lshl_b32 s2, s4, 1
	s_add_u32 s8, s8, s2
	s_addc_u32 s9, s9, 0
	s_add_u32 s8, s8, 0x1000
	s_addc_u32 s9, s9, 0
	v_lshlrev_b32_e32 v77, 4, v76
	v_lshlrev_b32_e32 v78, 3, v76
	v_lshrrev_b32_e32 v79, 4, v76
	v_and_b32_e32 v83, 15, v76
	v_lshlrev_b32_e32 v79, 6, v79
	v_lshlrev_b32_e32 v83, 3, v83
	v_lshl_add_u32 v83, v79, 7, v83
	v_mov_b32_e32 v0, 0
	v_mov_b32_e32 v1, 0
	v_mov_b32_e32 v2, 0
	v_mov_b32_e32 v3, 0
	v_mov_b32_e32 v4, 0
	v_mov_b32_e32 v5, 0
	v_mov_b32_e32 v6, 0
	v_mov_b32_e32 v7, 0
	v_mov_b32_e32 v8, 0
	v_mov_b32_e32 v9, 0
	v_mov_b32_e32 v10, 0
	v_mov_b32_e32 v11, 0
	v_mov_b32_e32 v12, 0
	v_mov_b32_e32 v13, 0
	v_mov_b32_e32 v14, 0
	v_mov_b32_e32 v15, 0
	v_mov_b32_e32 v16, 0
	v_mov_b32_e32 v17, 0
	v_mov_b32_e32 v18, 0
	v_mov_b32_e32 v19, 0
	v_mov_b32_e32 v20, 0
	v_mov_b32_e32 v21, 0
	v_mov_b32_e32 v22, 0
	v_mov_b32_e32 v23, 0
	s_barrier
	ds_read_b128 v[32:35], v77
	ds_read_b128 v[36:39], v77 offset:1024
	ds_read_b128 v[40:43], v77 offset:2048
	ds_read_b128 v[44:47], v77 offset:3072
	ds_read2st64_b64 v[96:99], v78 offset0:16 offset1:17
	ds_read_b128 v[64:67], v79 offset:9728
	ds_read_b128 v[68:71], v79 offset:9744
	ds_read_b128 v[72:75], v79 offset:9760
	ds_read_b128 v[88:91], v79 offset:9776
	ds_read2st64_b64 v[48:51], v78 offset0:12 offset1:8
	ds_read2st64_b64 v[52:55], v78 offset0:13 offset1:9
	ds_read2st64_b64 v[56:59], v78 offset0:14 offset1:10
	ds_read2st64_b64 v[60:63], v78 offset0:15 offset1:11
	ds_read_b64 v[92:93], v78 offset:9216
	s_movk_i32 s10, 0x2800
	s_mov_b32 s11, 0
	s_waitcnt lgkmcnt(9)
	v_lshlrev_b32_e32 v24, 16, v96
	v_and_b32_e32 v25, 0xffff0000, v96
	v_lshlrev_b32_e32 v26, 16, v97
	v_and_b32_e32 v27, 0xffff0000, v97
	v_lshlrev_b32_e32 v28, 16, v98
	v_and_b32_e32 v29, 0xffff0000, v98
	v_lshlrev_b32_e32 v30, 16, v99
	v_and_b32_e32 v31, 0xffff0000, v99
; __device__ __forceinline__ void p3_rwkv_state(Frame& F, const Args& a) {
;     ...
;         for (int n = 0; n < NC; n += 2) { SP_STEP(C, N, n); SP_STEP(N, C, n + 1); }
.Lscan_loop:
	v_add_u32_e32 v80, s10, v77
	v_add_u32_e32 v81, s10, v78
	v_add_u32_e32 v82, s10, v79
	s_add_i32 s10, s10, 0x2800
	s_cmp_eq_u32 s10, 0x25800
	s_cselect_b32 s10, 0, s10
	v_mfma_f32_16x16x32_bf16 v[24:27], v[32:35], v[16:19], v[24:27]
	v_mfma_f32_16x16x32_bf16 v[28:31], v[40:43], v[16:19], v[28:31]
	v_mfma_f32_16x16x32_bf16 v[24:27], v[36:39], v[20:23], v[24:27]
	v_mfma_f32_16x16x32_bf16 v[28:31], v[44:47], v[20:23], v[28:31]
	ds_read_b128 v[32:35], v80
	ds_read_b128 v[36:39], v80 offset:1024
	ds_read_b128 v[40:43], v80 offset:2048
	ds_read_b128 v[44:47], v80 offset:3072
	ds_read2st64_b64 v[96:99], v81 offset0:16 offset1:17
	s_waitcnt lgkmcnt(10)
	v_mul_f32_e32 v0, v64, v0
	v_mul_f32_e32 v1, v65, v1
	v_mul_f32_e32 v2, v66, v2
	v_mul_f32_e32 v3, v67, v3
	v_mul_f32_e32 v4, v68, v4
	v_mul_f32_e32 v5, v69, v5
	v_mul_f32_e32 v6, v70, v6
	v_mul_f32_e32 v7, v71, v7
	v_mul_f32_e32 v8, v72, v8
	v_mul_f32_e32 v9, v73, v9
	v_mul_f32_e32 v10, v74, v10
	v_mul_f32_e32 v11, v75, v11
	v_mul_f32_e32 v12, v88, v12
	v_mul_f32_e32 v13, v89, v13
	v_mul_f32_e32 v14, v90, v14
	v_mul_f32_e32 v15, v91, v15
	ds_read_b128 v[64:67], v82 offset:9728
	ds_read_b128 v[68:71], v82 offset:9744
	ds_read_b128 v[72:75], v82 offset:9760
	ds_read_b128 v[88:91], v82 offset:9776
	v_cvt_pk_bf16_f32 v94, v24, v25
	v_cvt_pk_bf16_f32 v95, v26, v27
	s_waitcnt lgkmcnt(9)
	s_nop 1
	v_mfma_f32_16x16x32_bf16 v[0:3], v[48:51], v[92:95], v[0:3]
	v_mfma_f32_16x16x32_bf16 v[4:7], v[52:55], v[92:95], v[4:7]
	v_mfma_f32_16x16x32_bf16 v[8:11], v[56:59], v[92:95], v[8:11]
	v_mfma_f32_16x16x32_bf16 v[12:15], v[60:63], v[92:95], v[12:15]
	v_cvt_pk_bf16_f32 v84, v28, v29
	v_cvt_pk_bf16_f32 v85, v30, v31
	ds_read2st64_b64 v[48:51], v81 offset0:12 offset1:8
	ds_read2st64_b64 v[52:55], v81 offset0:13 offset1:9
	ds_read2st64_b64 v[56:59], v81 offset0:14 offset1:10
	ds_read2st64_b64 v[60:63], v81 offset0:15 offset1:11
	ds_read_b64 v[92:93], v81 offset:9216
	global_store_short v83, v84, s[8:9] offset:-4096
	global_store_short_d16_hi v83, v84, s[8:9] offset:-2048
	global_store_short v83, v85, s[8:9]
	global_store_short_d16_hi v83, v85, s[8:9] offset:2048
	s_add_u32 s8, s8, 0x8000
	s_addc_u32 s9, s9, 0
	s_waitcnt lgkmcnt(9)
	v_lshlrev_b32_e32 v24, 16, v96
	v_and_b32_e32 v25, 0xffff0000, v96
	v_lshlrev_b32_e32 v26, 16, v97
	v_and_b32_e32 v27, 0xffff0000, v97
	v_lshlrev_b32_e32 v28, 16, v98
	v_and_b32_e32 v29, 0xffff0000, v98
	v_lshlrev_b32_e32 v30, 16, v99
	v_and_b32_e32 v31, 0xffff0000, v99
	v_cvt_pk_bf16_f32 v16, v0, v1
	v_cvt_pk_bf16_f32 v17, v2, v3
	v_cvt_pk_bf16_f32 v18, v4, v5
	v_cvt_pk_bf16_f32 v19, v6, v7
	v_cvt_pk_bf16_f32 v20, v8, v9
	v_cvt_pk_bf16_f32 v21, v10, v11
	v_cvt_pk_bf16_f32 v22, v12, v13
	v_cvt_pk_bf16_f32 v23, v14, v15
	v_add_u32_e32 v80, s10, v77
	v_add_u32_e32 v81, s10, v78
	v_add_u32_e32 v82, s10, v79
	s_add_i32 s10, s10, 0x2800
	s_cmp_eq_u32 s10, 0x25800
	s_cselect_b32 s10, 0, s10
	v_mfma_f32_16x16x32_bf16 v[24:27], v[32:35], v[16:19], v[24:27]
	v_mfma_f32_16x16x32_bf16 v[28:31], v[40:43], v[16:19], v[28:31]
	v_mfma_f32_16x16x32_bf16 v[24:27], v[36:39], v[20:23], v[24:27]
	v_mfma_f32_16x16x32_bf16 v[28:31], v[44:47], v[20:23], v[28:31]
	ds_read_b128 v[32:35], v80
	ds_read_b128 v[36:39], v80 offset:1024
	ds_read_b128 v[40:43], v80 offset:2048
	ds_read_b128 v[44:47], v80 offset:3072
	ds_read2st64_b64 v[96:99], v81 offset0:16 offset1:17
	s_waitcnt lgkmcnt(10)
	v_mul_f32_e32 v0, v64, v0
	v_mul_f32_e32 v1, v65, v1
	v_mul_f32_e32 v2, v66, v2
	v_mul_f32_e32 v3, v67, v3
	v_mul_f32_e32 v4, v68, v4
	v_mul_f32_e32 v5, v69, v5
	v_mul_f32_e32 v6, v70, v6
	v_mul_f32_e32 v7, v71, v7
	v_mul_f32_e32 v8, v72, v8
	v_mul_f32_e32 v9, v73, v9
	v_mul_f32_e32 v10, v74, v10
	v_mul_f32_e32 v11, v75, v11
	v_mul_f32_e32 v12, v88, v12
	v_mul_f32_e32 v13, v89, v13
	v_mul_f32_e32 v14, v90, v14
	v_mul_f32_e32 v15, v91, v15
	ds_read_b128 v[64:67], v82 offset:9728
	ds_read_b128 v[68:71], v82 offset:9744
	ds_read_b128 v[72:75], v82 offset:9760
	ds_read_b128 v[88:91], v82 offset:9776
	v_cvt_pk_bf16_f32 v94, v24, v25
	v_cvt_pk_bf16_f32 v95, v26, v27
	s_waitcnt lgkmcnt(9)
	s_nop 1
	v_mfma_f32_16x16x32_bf16 v[0:3], v[48:51], v[92:95], v[0:3]
	v_mfma_f32_16x16x32_bf16 v[4:7], v[52:55], v[92:95], v[4:7]
	v_mfma_f32_16x16x32_bf16 v[8:11], v[56:59], v[92:95], v[8:11]
	v_mfma_f32_16x16x32_bf16 v[12:15], v[60:63], v[92:95], v[12:15]
	v_cvt_pk_bf16_f32 v84, v28, v29
	v_cvt_pk_bf16_f32 v85, v30, v31
	ds_read2st64_b64 v[48:51], v81 offset0:12 offset1:8
	ds_read2st64_b64 v[52:55], v81 offset0:13 offset1:9
	ds_read2st64_b64 v[56:59], v81 offset0:14 offset1:10
	ds_read2st64_b64 v[60:63], v81 offset0:15 offset1:11
	ds_read_b64 v[92:93], v81 offset:9216
	global_store_short v83, v84, s[8:9] offset:-4096
	global_store_short_d16_hi v83, v84, s[8:9] offset:-2048
	global_store_short v83, v85, s[8:9]
	global_store_short_d16_hi v83, v85, s[8:9] offset:2048
	s_add_u32 s8, s8, 0x8000
	s_addc_u32 s9, s9, 0
	s_waitcnt lgkmcnt(9)
	v_lshlrev_b32_e32 v24, 16, v96
	v_and_b32_e32 v25, 0xffff0000, v96
	v_lshlrev_b32_e32 v26, 16, v97
	v_and_b32_e32 v27, 0xffff0000, v97
	v_lshlrev_b32_e32 v28, 16, v98
	v_and_b32_e32 v29, 0xffff0000, v98
	v_lshlrev_b32_e32 v30, 16, v99
	v_and_b32_e32 v31, 0xffff0000, v99
	v_cvt_pk_bf16_f32 v16, v0, v1
	v_cvt_pk_bf16_f32 v17, v2, v3
	v_cvt_pk_bf16_f32 v18, v4, v5
	v_cvt_pk_bf16_f32 v19, v6, v7
	v_cvt_pk_bf16_f32 v20, v8, v9
	v_cvt_pk_bf16_f32 v21, v10, v11
	v_cvt_pk_bf16_f32 v22, v12, v13
	v_cvt_pk_bf16_f32 v23, v14, v15
	s_barrier
	s_add_i32 s11, s11, 2
	s_cmpk_lt_u32 s11, 0x400
	s_cbranch_scc1 .Lscan_loop
	s_branch .LBB0_456
.LBB0_456:
	s_waitcnt vmcnt(0)
	s_waitcnt lgkmcnt(0)
	s_barrier
	s_branch .LBB0_457
.Lrw_late_entry:
	s_mov_b32 s98, 1
	v_readlane_b32 s36, v255, 8
	v_readlane_b32 s37, v255, 9
	v_readlane_b32 s38, v255, 10
	v_readlane_b32 s39, v255, 11
	v_readlane_b32 s40, v255, 12
	v_readlane_b32 s41, v255, 13
	v_readlane_b32 s42, v255, 14
	v_readlane_b32 s43, v255, 15
	v_readlane_b32 s44, v255, 16
	v_readlane_b32 s45, v255, 17
	v_readlane_b32 s46, v255, 18
	v_readlane_b32 s47, v255, 19
	v_readlane_b32 s48, v255, 20
	v_readlane_b32 s49, v255, 21
	v_readlane_b32 s50, v255, 22
	v_readlane_b32 s51, v255, 23
	s_add_u32 s6, s90, 0x3300000
	s_addc_u32 s7, s91, 0
	s_add_u32 s8, s90, 0x3380000
	s_addc_u32 s9, s91, 0
	s_add_u32 s14, s90, 0x8000000
	s_addc_u32 s15, s91, 0
	v_mbcnt_lo_u32_b32 v10, -1, 0
	v_mbcnt_hi_u32_b32 v10, -1, v10
	v_and_b32_e32 v11, 15, v10
	v_lshlrev_b32_e32 v0, 4, v10
	s_nop 4
	s_branch .Lrw_again
.Lrw_late_done:
	s_mov_b32 s98, 2
	v_mbcnt_lo_u32_b32 v76, -1, 0
	v_mbcnt_hi_u32_b32 v76, -1, v76

; __global__ void __launch_bounds__(NTHR, 2) hybrid_fwd(Args args) {
	.amdhsa_kernel _Z10hybrid_fwd4Args
		.amdhsa_group_segment_fixed_size 0
		.amdhsa_private_segment_fixed_size 0
		.amdhsa_kernarg_size 480
		.amdhsa_user_sgpr_count 2
		.amdhsa_user_sgpr_dispatch_ptr 0
		.amdhsa_user_sgpr_queue_ptr 0
		.amdhsa_user_sgpr_kernarg_segment_ptr 1
		.amdhsa_user_sgpr_dispatch_id 0
		.amdhsa_user_sgpr_kernarg_preload_length 0
		.amdhsa_user_sgpr_kernarg_preload_offset 0
		.amdhsa_user_sgpr_private_segment_size 0
		.amdhsa_uses_dynamic_stack 0
		.amdhsa_enable_private_segment 0
		.amdhsa_system_sgpr_workgroup_id_x 1
		.amdhsa_system_sgpr_workgroup_id_y 0
		.amdhsa_system_sgpr_workgroup_id_z 0
		.amdhsa_system_sgpr_workgroup_info 0
		.amdhsa_system_vgpr_workitem_id 2
		.amdhsa_next_free_vgpr 256
		.amdhsa_next_free_sgpr 102
		.amdhsa_accum_offset 256
		.amdhsa_reserve_vcc 1
		.amdhsa_float_round_mode_32 0
		.amdhsa_float_round_mode_16_64 0
		.amdhsa_float_denorm_mode_32 3
		.amdhsa_float_denorm_mode_16_64 3
		.amdhsa_dx10_clamp 1
		.amdhsa_ieee_mode 1
		.amdhsa_fp16_overflow 0
		.amdhsa_tg_split 0
		.amdhsa_exception_fp_ieee_invalid_op 0
		.amdhsa_exception_fp_denorm_src 0
		.amdhsa_exception_fp_ieee_div_zero 0
		.amdhsa_exception_fp_ieee_overflow 0
		.amdhsa_exception_fp_ieee_underflow 0
		.amdhsa_exception_fp_ieee_inexact 0
		.amdhsa_exception_int_div_zero 0
	.end_amdhsa_kernel

; __global__ void __launch_bounds__(NTHR, 2) hybrid_fwd(Args args) {
amdhsa.kernels:
  - .agpr_count:     0
    .args:
      - .offset:         0
        .size:           224
        .value_kind:     by_value
      - .offset:         224
        .size:           4
        .value_kind:     hidden_block_count_x
      - .offset:         228
        .size:           4
        .value_kind:     hidden_block_count_y
      - .offset:         232
        .size:           4
        .value_kind:     hidden_block_count_z
      - .offset:         236
        .size:           2
        .value_kind:     hidden_group_size_x
      - .offset:         238
        .size:           2
        .value_kind:     hidden_group_size_y
      - .offset:         240
        .size:           2
        .value_kind:     hidden_group_size_z
      - .offset:         242
        .size:           2
        .value_kind:     hidden_remainder_x
      - .offset:         244
        .size:           2
        .value_kind:     hidden_remainder_y
      - .offset:         246
        .size:           2
        .value_kind:     hidden_remainder_z
      - .offset:         264
        .size:           8
        .value_kind:     hidden_global_offset_x
      - .offset:         272
        .size:           8
        .value_kind:     hidden_global_offset_y
      - .offset:         280
        .size:           8
        .value_kind:     hidden_global_offset_z
      - .offset:         288
        .size:           2
        .value_kind:     hidden_grid_dims
      - .offset:         312
        .size:           8
        .value_kind:     hidden_multigrid_sync_arg
      - .offset:         344
        .size:           4
        .value_kind:     hidden_dynamic_lds_size
    .group_segment_fixed_size: 0
    .kernarg_segment_align: 8
    .kernarg_segment_size: 480
    .language:       OpenCL C
    .language_version:
      - 2
      - 0
    .max_flat_workgroup_size: 512
    .name:           _Z10hybrid_fwd4Args
    .private_segment_fixed_size: 0
    .sgpr_count:     108
    .sgpr_spill_count: 69
    .symbol:         _Z10hybrid_fwd4Args.kd
    .uniform_work_group_size: 1
    .uses_dynamic_stack: false
    .vgpr_count:     256
    .vgpr_spill_count: 0
    .wavefront_size: 64
